# v29 + P5 unit order: per-row-group column-tile rotation table (K/V-store tiles uniform over rounds, none in the last round)
# speedup vs baseline: 1.0109x; 1.0001x over previous
.LBB0_510:
	s_ashr_i32 s4, s6, 3
	s_add_i32 s4, s8, s4
	s_mul_hi_i32 s5, s4, 0x3e0f83e1
	s_lshr_b32 s6, s5, 31
	s_ashr_i32 s5, s5, 6
	s_add_i32 s5, s5, s6
	s_lshl_b32 s6, s5, 3
	s_sub_i32 s7, 0x44, s6
	s_mulk_i32 s5, 0x108
	s_min_u32 s7, s7, 8
	s_sub_i32 s9, s4, s5
	s_sext_i32_i16 s4, s9
	v_cvt_f32_ubyte0_e32 v1, s7
	v_cvt_f32_i32_e32 v0, s4
	v_rcp_iflag_f32_e32 v2, v1
	s_ashr_i32 s4, s4, 30
	s_or_b32 s8, s4, 1
	v_mul_f32_e32 v2, v0, v2
	v_trunc_f32_e32 v2, v2
	v_fma_f32 v0, -v2, v1, v0
	v_cvt_i32_f32_e32 v2, v2
	v_cmp_ge_f32_e64 s[4:5], |v0|, v1
	s_and_b64 s[4:5], s[4:5], exec
	s_cselect_b32 s4, s8, 0
	v_readfirstlane_b32 s5, v2
	s_add_i32 s4, s5, s4
	s_sext_i32_i16 s8, s4
	s_mul_i32 s4, s4, s7
	s_sub_i32 s4, s9, s4
	s_sext_i32_i16 s4, s4
	s_add_i32 s6, s6, s4
	s_lshr_b32 s7, s6, 3
	s_mul_i32 s7, s7, 6
	s_mov_b32 s4, 0xcc5d9044
	s_mov_b32 s5, 0x1304a1
	s_lshr_b64 s[4:5], s[4:5], s7
	s_and_b32 s7, s4, 63
	s_add_i32 s8, s8, s7
	s_cmp_gt_i32 s8, 32
	s_cselect_b32 s7, 33, 0
	s_sub_i32 s8, s8, s7

.LBB0_522:
	s_ashr_i32 s7, s7, 3
	s_add_i32 s7, s20, s7
	s_mul_hi_i32 s9, s7, 0x3e0f83e1
	s_lshr_b32 s18, s9, 31
	s_ashr_i32 s9, s9, 6
	s_add_i32 s9, s9, s18
	s_lshl_b32 s19, s9, 3
	s_sub_i32 s18, 0x44, s19
	s_min_i32 s20, s18, 8
	s_abs_i32 s18, s20
	v_cvt_f32_u32_e32 v0, s18
	s_sub_i32 s22, 0, s18
	s_mulk_i32 s9, 0x108
	s_sub_i32 s7, s7, s9
	v_rcp_iflag_f32_e32 v0, v0
	s_abs_i32 s9, s7
	s_xor_b32 s21, s7, s20
	s_ashr_i32 s21, s21, 31
	v_mul_f32_e32 v0, 0x4f7ffffe, v0
	v_cvt_u32_f32_e32 v0, v0
	s_nop 0
	v_readfirstlane_b32 s23, v0
	s_mul_i32 s22, s22, s23
	s_mul_hi_u32 s22, s23, s22
	s_add_i32 s23, s23, s22
	s_mul_hi_u32 s22, s9, s23
	s_mul_i32 s23, s22, s18
	s_sub_i32 s9, s9, s23
	s_add_i32 s24, s22, 1
	s_sub_i32 s23, s9, s18
	s_cmp_ge_u32 s9, s18
	s_cselect_b32 s22, s24, s22
	s_cselect_b32 s9, s23, s9
	s_add_i32 s23, s22, 1
	s_cmp_ge_u32 s9, s18
	s_cselect_b32 s9, s23, s22
	s_xor_b32 s9, s9, s21
	s_sub_i32 s18, s9, s21
	s_mul_i32 s9, s18, s20
	s_sub_i32 s7, s7, s9
	s_add_i32 s20, s19, s7
	s_lshr_b32 s9, s20, 3
	s_mul_i32 s9, s9, 6
	s_mov_b32 s22, 0xcc5d9044
	s_mov_b32 s23, 0x1304a1
	s_lshr_b64 s[22:23], s[22:23], s9
	s_and_b32 s9, s22, 63
	s_add_i32 s18, s18, s9
	s_cmp_gt_i32 s18, 32
	s_cselect_b32 s9, 33, 0
	s_sub_i32 s18, s18, s9
